# attention loop: K/V fragment LDS reads issued 3-8 MFMAs ahead with counted lgkmcnt (K fragments of a QK^T all at the stage head), on top of the interleaved exp blocks
# speedup vs baseline: 1.0560x; 1.0066x over previous
; #define SBAR() __builtin_amdgcn_sched_barrier(0)
; #define SLOAD(i, k0) do { const char* vt_ = (const char*)Vh + (size_t)(k0) * 256; const char* kt_ = (const char*)Kh + (size_t)(k0) * 128; \
;     sr_[i].vs0 = *reinterpret_cast<const bf16x8*>(vt_ + voff0); sr_[i].vs1 = *reinterpret_cast<const bf16x8*>(vt_ + 32 * 256 + voff0); \
;     sr_[i].ks0 = *reinterpret_cast<const bf16x8*>(kt_ + koff0); } while (0)
; #define SBAR() __builtin_amdgcn_sched_barrier(0)
; __device__ __forceinline__ void qkt(f32x16& p0, f32x16& p1, const char* Ks, const bf16x8* qr, int r32, int hi) {
;     p0 = f32x16{}; p1 = f32x16{};
; #pragma unroll
;     for (int d0 = 0; d0 < 4; ++d0) { const int cb = (d0 * 16 + hi * 8) * 2;
;         const bf16x8 b0 = *reinterpret_cast<const bf16x8*>(Ks + KSWZ64(r32, cb));
;         const bf16x8 b1 = *reinterpret_cast<const bf16x8*>(Ks + KSWZ64(32 + r32, cb));
;         p0 = __builtin_amdgcn_mfma_f32_32x32x16_bf16(b0, qr[d0], p0, 0, 0, 0);
;         p1 = __builtin_amdgcn_mfma_f32_32x32x16_bf16(b1, qr[d0], p1, 0, 0, 0); }
; }
; template <int KS> __device__ __forceinline__ void pv_ks(f32x16* o, int vb, bf16x8 pa) {
;     const s16x4 l0 = tr_read<v_rd_off(0, KS, 0)>(vb), h0 = tr_read<v_rd_off(0, KS, 1)>(vb), l1 = tr_read<v_rd_off(1, KS, 0)>(vb), h1 = tr_read<v_rd_off(1, KS, 1)>(vb);
;     const s16x4 l2 = tr_read<v_rd_off(2, KS, 0)>(vb), h2 = tr_read<v_rd_off(2, KS, 1)>(vb), l3 = tr_read<v_rd_off(3, KS, 0)>(vb), h3 = tr_read<v_rd_off(3, KS, 1)>(vb);
;     asm volatile("s_waitcnt lgkmcnt(0)" ::: "memory"); SBAR();
;     ...
;     o[0] = __builtin_amdgcn_mfma_f32_32x32x16_bf16(pa, PK(l0, h0), o[0], 0, 0, 0);
;     o[1] = __builtin_amdgcn_mfma_f32_32x32x16_bf16(pa, PK(l1, h1), o[1], 0, 0, 0);
;     o[2] = __builtin_amdgcn_mfma_f32_32x32x16_bf16(pa, PK(l2, h2), o[2], 0, 0, 0);
;     o[3] = __builtin_amdgcn_mfma_f32_32x32x16_bf16(pa, PK(l3, h3), o[3], 0, 0, 0);
;     ...
; }
; __device__ __forceinline__ void attn_unit(const bf16* __restrict__ Qb, const bf16* __restrict__ Kh, const bf16* __restrict__ Vh, bf16* __restrict__ Ob, int seq, char* lds) {
;     ...
;         SBAR(); qkt(pB0, pB1, K_lds + SHM_K, qr, r32, hi); pv_ks<0>(o, vb0, pa0); SBAR();
;         softHalf(pA1, l_reg, pa2, pa3); SBAR();
;         SLOAD(SO, (j + 1) * KVBLK); SBAR();
;         pv_ks<1>(o, vb0, pa1); pv_ks<2>(o, vb0, pa2); pv_ks<3>(o, vb0, pa3); SBAR();
;         softHalf(pB0, l_reg, pa0, pa1); SBAR();
.LBB0_531:
	ds_read_b128 v[82:85], v157 offset:40960
	ds_read_b128 v[86:89], v157 offset:45056
	ds_read_b128 v[164:167], v159 offset:40960
	ds_read_b128 v[168:171], v159 offset:45056
	ds_read_b128 v[188:191], v162 offset:40960
	ds_read_b128 v[230:233], v162 offset:45056
	ds_read_b128 v[234:237], v163 offset:40960
	ds_read_b128 v[242:245], v163 offset:45056
	v_exp_f32_e32 v66, v66
	v_exp_f32_e32 v67, v67
	v_exp_f32_e32 v68, v68
	v_exp_f32_e32 v69, v69
	s_waitcnt lgkmcnt(7)
	v_mfma_f32_32x32x16_bf16 v[98:113], v[82:85], v[126:129], 0
	v_exp_f32_e32 v70, v70
	v_add_f32_e32 v179, 0, v66
	v_exp_f32_e32 v71, v71
	s_waitcnt lgkmcnt(6)
	v_mfma_f32_32x32x16_bf16 v[82:97], v[86:89], v[126:129], 0
	v_add_f32_e32 v179, v67, v179
	v_exp_f32_e32 v72, v72
	v_add_f32_e32 v179, v68, v179
	v_exp_f32_e32 v73, v73
	s_waitcnt lgkmcnt(5)
	v_mfma_f32_32x32x16_bf16 v[98:113], v[164:167], v[122:125], v[98:113]
	v_add_f32_e32 v179, v69, v179
	v_exp_f32_e32 v74, v74
	v_add_f32_e32 v179, v70, v179
	v_exp_f32_e32 v75, v75
	s_waitcnt lgkmcnt(4)
	v_mfma_f32_32x32x16_bf16 v[82:97], v[168:171], v[122:125], v[82:97]
	ds_read_b64_tr_b16 v[172:173], v156 offset:0
	ds_read_b64_tr_b16 v[174:175], v156 offset:0x800
	ds_read_b64_tr_b16 v[164:165], v156 offset:0x200
	ds_read_b64_tr_b16 v[166:167], v156 offset:0xa00
	ds_read_b64_tr_b16 v[180:181], v156 offset:0x400
	ds_read_b64_tr_b16 v[182:183], v156 offset:0xc00
	ds_read_b64_tr_b16 v[184:185], v156 offset:0x600
	ds_read_b64_tr_b16 v[186:187], v156 offset:0xe00
	v_add_f32_e32 v179, v71, v179
	v_exp_f32_e32 v76, v76
	v_add_f32_e32 v179, v72, v179
	s_waitcnt lgkmcnt(11)
	v_mfma_f32_32x32x16_bf16 v[98:113], v[188:191], v[118:121], v[98:113]
	v_exp_f32_e32 v77, v77
	v_add_f32_e32 v179, v73, v179
	v_exp_f32_e32 v78, v78
	v_add_f32_e32 v179, v74, v179
	s_waitcnt lgkmcnt(10)
	v_mfma_f32_32x32x16_bf16 v[82:97], v[230:233], v[118:121], v[82:97]
	v_exp_f32_e32 v79, v79
	v_add_f32_e32 v179, v75, v179
	v_exp_f32_e32 v80, v80
	s_waitcnt lgkmcnt(9)
	v_mfma_f32_32x32x16_bf16 v[98:113], v[234:237], v[114:117], v[98:113]
	v_add_f32_e32 v179, v76, v179
	v_exp_f32_e32 v81, v81
	v_add_f32_e32 v179, v77, v179
	v_add_f32_e32 v179, v78, v179
	v_add_f32_e32 v179, v79, v179
	s_waitcnt lgkmcnt(8)
	v_mfma_f32_32x32x16_bf16 v[82:97], v[242:245], v[114:117], v[82:97]
	v_add_f32_e32 v179, v80, v179
	v_add_f32_e32 v179, v81, v179
	v_cvt_pk_bf16_f32 v66, v66, v67
	v_cvt_pk_bf16_f32 v67, v68, v69
	s_waitcnt lgkmcnt(6)
	v_mfma_f32_32x32x16_bf16 v[2:17], v[134:137], v[172:175], v[2:17]
	ds_read_b64_tr_b16 v[188:189], v156 offset:0x1000
	ds_read_b64_tr_b16 v[190:191], v156 offset:0x1800
	ds_read_b64_tr_b16 v[230:231], v156 offset:0x1200
	ds_read_b64_tr_b16 v[232:233], v156 offset:0x1a00
	ds_read_b64_tr_b16 v[234:235], v156 offset:0x1400
	ds_read_b64_tr_b16 v[236:237], v156 offset:0x1c00
	ds_read_b64_tr_b16 v[242:243], v156 offset:0x1600
	ds_read_b64_tr_b16 v[244:245], v156 offset:0x1e00
	v_cvt_pk_bf16_f32 v68, v70, v71
	v_cvt_pk_bf16_f32 v69, v72, v73
	v_cvt_pk_bf16_f32 v70, v74, v75
	v_cvt_pk_bf16_f32 v71, v76, v77
	v_cvt_pk_bf16_f32 v72, v78, v79
	s_waitcnt lgkmcnt(12)
	v_mfma_f32_32x32x16_bf16 v[18:33], v[134:137], v[164:167], v[18:33]
	v_cvt_pk_bf16_f32 v73, v80, v81
	v_add_f32_e32 v221, v139, v179
	v_permlane32_swap_b32_e32 v66, v68
	s_waitcnt lgkmcnt(10)
	v_mfma_f32_32x32x16_bf16 v[34:49], v[134:137], v[180:183], v[34:49]
	v_permlane32_swap_b32_e32 v67, v69
	v_permlane32_swap_b32_e32 v70, v72
	v_permlane32_swap_b32_e32 v71, v73
	s_waitcnt lgkmcnt(8)
	v_mfma_f32_32x32x16_bf16 v[50:65], v[134:137], v[184:187], v[50:65]
	v_lshl_add_u64 v[136:137], s[30:31], 0, v[148:149]
	v_add_co_u32_e32 v74, vcc, s40, v136
	v_lshl_add_u64 v[150:151], s[30:31], 0, v[146:147]
	s_nop 0
	v_addc_co_u32_e32 v75, vcc, 0, v137, vcc
	v_add_co_u32_e32 v78, vcc, s41, v136
	s_nop 1
	v_addc_co_u32_e32 v79, vcc, 0, v137, vcc
	v_add_co_u32_e32 v164, vcc, s42, v150
	global_load_dwordx4 v[74:77], v[74:75], off
	s_waitcnt lgkmcnt(6)
	v_mfma_f32_32x32x16_bf16 v[2:17], v[130:133], v[188:191], v[2:17]
	ds_read_b64_tr_b16 v[168:169], v156 offset:0x2000
	ds_read_b64_tr_b16 v[170:171], v156 offset:0x2800
	ds_read_b64_tr_b16 v[172:173], v156 offset:0x2200
	ds_read_b64_tr_b16 v[174:175], v156 offset:0x2a00
	ds_read_b64_tr_b16 v[180:181], v156 offset:0x2400
	ds_read_b64_tr_b16 v[182:183], v156 offset:0x2c00
	ds_read_b64_tr_b16 v[184:185], v156 offset:0x2600
	ds_read_b64_tr_b16 v[186:187], v156 offset:0x2e00
	s_nop 0
	global_load_dwordx4 v[78:81], v[78:79], off
	v_addc_co_u32_e32 v165, vcc, 0, v151, vcc
	global_load_dwordx4 v[164:167], v[164:165], off
	v_exp_f32_e32 v220, v98
	s_waitcnt lgkmcnt(12)
	v_mfma_f32_32x32x16_bf16 v[18:33], v[130:133], v[230:233], v[18:33]
	v_exp_f32_e32 v177, v99
	v_exp_f32_e32 v193, v100
	v_exp_f32_e32 v195, v101
	s_waitcnt lgkmcnt(10)
	v_mfma_f32_32x32x16_bf16 v[34:49], v[130:133], v[234:237], v[34:49]
	v_exp_f32_e32 v197, v102
	v_exp_f32_e32 v199, v103
	v_exp_f32_e32 v201, v104
	v_exp_f32_e32 v203, v105
	s_waitcnt lgkmcnt(8)
	v_mfma_f32_32x32x16_bf16 v[50:65], v[130:133], v[242:245], v[50:65]
	v_cvt_pk_bf16_f32 v222, v220, v177
	v_cvt_pk_bf16_f32 v223, v193, v195
	v_cvt_pk_bf16_f32 v224, v197, v199
	v_cvt_pk_bf16_f32 v225, v201, v203
	v_exp_f32_e32 v205, v106
	s_waitcnt lgkmcnt(6)
	v_mfma_f32_32x32x16_bf16 v[2:17], v[66:69], v[168:171], v[2:17]
	ds_read_b64_tr_b16 v[188:189], v156 offset:0x3000
	ds_read_b64_tr_b16 v[190:191], v156 offset:0x3800
	ds_read_b64_tr_b16 v[230:231], v156 offset:0x3200
	ds_read_b64_tr_b16 v[232:233], v156 offset:0x3a00
	ds_read_b64_tr_b16 v[234:235], v156 offset:0x3400
	ds_read_b64_tr_b16 v[236:237], v156 offset:0x3c00
	ds_read_b64_tr_b16 v[242:243], v156 offset:0x3600
	ds_read_b64_tr_b16 v[244:245], v156 offset:0x3e00
	v_exp_f32_e32 v207, v107
	v_exp_f32_e32 v209, v108
	v_exp_f32_e32 v211, v109
	s_waitcnt lgkmcnt(12)
; #define SBAR() __builtin_amdgcn_sched_barrier(0)
; #define SWAIT() asm volatile("s_waitcnt vmcnt(0)" ::: "memory")
; #define SBAR() __builtin_amdgcn_sched_barrier(0)
; __device__ __forceinline__ void qkt(f32x16& p0, f32x16& p1, const char* Ks, const bf16x8* qr, int r32, int hi) {
;     p0 = f32x16{}; p1 = f32x16{};
; #pragma unroll
;     for (int d0 = 0; d0 < 4; ++d0) { const int cb = (d0 * 16 + hi * 8) * 2;
;         const bf16x8 b0 = *reinterpret_cast<const bf16x8*>(Ks + KSWZ64(r32, cb));
;         const bf16x8 b1 = *reinterpret_cast<const bf16x8*>(Ks + KSWZ64(32 + r32, cb));
;         p0 = __builtin_amdgcn_mfma_f32_32x32x16_bf16(b0, qr[d0], p0, 0, 0, 0);
;         p1 = __builtin_amdgcn_mfma_f32_32x32x16_bf16(b1, qr[d0], p1, 0, 0, 0); }
; }
; template <int KS> __device__ __forceinline__ void pv_ks(f32x16* o, int vb, bf16x8 pa) {
;     const s16x4 l0 = tr_read<v_rd_off(0, KS, 0)>(vb), h0 = tr_read<v_rd_off(0, KS, 1)>(vb), l1 = tr_read<v_rd_off(1, KS, 0)>(vb), h1 = tr_read<v_rd_off(1, KS, 1)>(vb);
;     const s16x4 l2 = tr_read<v_rd_off(2, KS, 0)>(vb), h2 = tr_read<v_rd_off(2, KS, 1)>(vb), l3 = tr_read<v_rd_off(3, KS, 0)>(vb), h3 = tr_read<v_rd_off(3, KS, 1)>(vb);
;     asm volatile("s_waitcnt lgkmcnt(0)" ::: "memory"); SBAR();
;     ...
;     o[0] = __builtin_amdgcn_mfma_f32_32x32x16_bf16(pa, PK(l0, h0), o[0], 0, 0, 0);
;     o[1] = __builtin_amdgcn_mfma_f32_32x32x16_bf16(pa, PK(l1, h1), o[1], 0, 0, 0);
;     o[2] = __builtin_amdgcn_mfma_f32_32x32x16_bf16(pa, PK(l2, h2), o[2], 0, 0, 0);
;     o[3] = __builtin_amdgcn_mfma_f32_32x32x16_bf16(pa, PK(l3, h3), o[3], 0, 0, 0);
;     ...
; }
; __device__ __forceinline__ void attn_unit(const bf16* __restrict__ Qb, const bf16* __restrict__ Kh, const bf16* __restrict__ Vh, bf16* __restrict__ Ob, int seq, char* lds) {
;     ...
;         pv_ks<1>(o, vb0, pa1); pv_ks<2>(o, vb0, pa2); pv_ks<3>(o, vb0, pa3); SBAR();
;         softHalf(pB0, l_reg, pa0, pa1); SBAR();
;         __syncthreads(); SWAIT(); SWRITE(0, SE);
;         __syncthreads();
;         SBAR(); qkt(pA0, pA1, K_lds, qr, r32, hi); pv_ks<0>(o, vb0 + SHM_V, pa0); SBAR();
;         softHalf(pB1, l_reg, pa2, pa3); SBAR();
;         SLOAD(SE, (j + 2) * KVBLK); SBAR();
;         pv_ks<1>(o, vb0 + SHM_V, pa1); pv_ks<2>(o, vb0 + SHM_V, pa2); pv_ks<3>(o, vb0 + SHM_V, pa3); SBAR();
;         softHalf(pA0, l_reg, pa0, pa1); SBAR();
	v_mfma_f32_32x32x16_bf16 v[18:33], v[66:69], v[172:175], v[18:33]
	v_exp_f32_e32 v213, v110
	v_exp_f32_e32 v215, v111
	v_exp_f32_e32 v217, v112
	s_waitcnt lgkmcnt(10)
	v_mfma_f32_32x32x16_bf16 v[34:49], v[66:69], v[180:183], v[34:49]
	v_exp_f32_e32 v219, v113
	v_add_f32_e32 v139, 0, v220
	v_add_f32_e32 v238, v177, v139
	v_add_f32_e32 v238, v193, v238
	v_add_f32_e32 v238, v195, v238
	v_add_f32_e32 v238, v197, v238
	s_waitcnt lgkmcnt(8)
	v_mfma_f32_32x32x16_bf16 v[50:65], v[66:69], v[184:187], v[50:65]
	v_add_f32_e32 v238, v199, v238
	v_add_f32_e32 v238, v201, v238
	v_add_f32_e32 v238, v203, v238
	v_add_f32_e32 v238, v205, v238
	v_add_f32_e32 v238, v207, v238
	v_add_f32_e32 v238, v209, v238
	s_waitcnt lgkmcnt(6)
	v_mfma_f32_32x32x16_bf16 v[2:17], v[70:73], v[188:191], v[2:17]
	v_add_f32_e32 v238, v211, v238
	v_add_f32_e32 v238, v213, v238
	v_add_f32_e32 v238, v215, v238
	v_add_f32_e32 v238, v217, v238
	v_add_f32_e32 v238, v219, v238
	v_add_f32_e32 v238, v221, v238
	s_waitcnt lgkmcnt(4)
	v_mfma_f32_32x32x16_bf16 v[18:33], v[70:73], v[230:233], v[18:33]
	v_permlane32_swap_b32_e32 v222, v224
	v_permlane32_swap_b32_e32 v223, v225
	v_cvt_pk_bf16_f32 v226, v205, v207
	v_cvt_pk_bf16_f32 v227, v209, v211
	v_cvt_pk_bf16_f32 v228, v213, v215
	s_waitcnt lgkmcnt(2)
	v_mfma_f32_32x32x16_bf16 v[34:49], v[70:73], v[234:237], v[34:49]
	v_cvt_pk_bf16_f32 v229, v217, v219
	s_nop 0
	v_permlane32_swap_b32_e32 v226, v228
	v_permlane32_swap_b32_e32 v227, v229
	s_waitcnt lgkmcnt(0)
	v_mfma_f32_32x32x16_bf16 v[50:65], v[70:73], v[242:245], v[50:65]
	s_barrier
	s_waitcnt vmcnt(0)
	s_waitcnt vmcnt(2)
	ds_write_b128 v160, v[74:77]
	s_waitcnt vmcnt(1)
	ds_write_b128 v161, v[78:81]
	s_waitcnt vmcnt(0)
	ds_write_b128 v158, v[164:167] offset:32768
	s_waitcnt lgkmcnt(0)
	s_barrier
	ds_read_b128 v[66:69], v157 offset:32768
	ds_read_b128 v[70:73], v157 offset:36864
	ds_read_b128 v[164:167], v159 offset:32768
	ds_read_b128 v[172:175], v159 offset:36864
	ds_read_b128 v[230:233], v162 offset:32768
	ds_read_b128 v[234:237], v162 offset:36864
	ds_read_b128 v[168:171], v163 offset:32768
	ds_read_b128 v[242:245], v163 offset:36864
	v_exp_f32_e32 v176, v82
	v_exp_f32_e32 v192, v83
	v_exp_f32_e32 v194, v84
	v_exp_f32_e32 v196, v85
	s_waitcnt lgkmcnt(7)
	v_mfma_f32_32x32x16_bf16 v[98:113], v[66:69], v[126:129], 0
	v_exp_f32_e32 v198, v86
	v_add_f32_e32 v82, v176, v138
	v_exp_f32_e32 v200, v87
	v_add_f32_e32 v82, v192, v82
	s_waitcnt lgkmcnt(6)
	v_mfma_f32_32x32x16_bf16 v[66:81], v[70:73], v[126:129], 0
	v_exp_f32_e32 v202, v88
	v_add_f32_e32 v82, v194, v82
	v_exp_f32_e32 v204, v89
	s_waitcnt lgkmcnt(5)
	v_mfma_f32_32x32x16_bf16 v[98:113], v[164:167], v[122:125], v[98:113]
	v_add_f32_e32 v82, v196, v82
	v_exp_f32_e32 v206, v90
	v_add_f32_e32 v82, v198, v82
	v_exp_f32_e32 v208, v91
	s_waitcnt lgkmcnt(4)
	v_mfma_f32_32x32x16_bf16 v[66:81], v[172:175], v[122:125], v[66:81]
	ds_read_b64_tr_b16 v[180:181], v141 offset:0
	ds_read_b64_tr_b16 v[182:183], v141 offset:0x800
	ds_read_b64_tr_b16 v[164:165], v141 offset:0x200
	ds_read_b64_tr_b16 v[166:167], v141 offset:0xa00
	ds_read_b64_tr_b16 v[184:185], v141 offset:0x400
	ds_read_b64_tr_b16 v[186:187], v141 offset:0xc00
	ds_read_b64_tr_b16 v[188:189], v141 offset:0x600
	ds_read_b64_tr_b16 v[190:191], v141 offset:0xe00
	v_add_f32_e32 v82, v200, v82
	v_exp_f32_e32 v210, v92
	v_add_f32_e32 v82, v202, v82
	s_waitcnt lgkmcnt(11)
	v_mfma_f32_32x32x16_bf16 v[98:113], v[230:233], v[118:121], v[98:113]
	v_exp_f32_e32 v212, v93
	v_add_f32_e32 v82, v204, v82
	v_exp_f32_e32 v214, v94
	v_add_f32_e32 v82, v206, v82
	s_waitcnt lgkmcnt(10)
	v_mfma_f32_32x32x16_bf16 v[66:81], v[234:237], v[118:121], v[66:81]
	v_exp_f32_e32 v216, v95
	v_add_f32_e32 v82, v208, v82
	v_exp_f32_e32 v218, v96
	v_add_f32_e32 v82, v210, v82
	s_waitcnt lgkmcnt(9)
	v_mfma_f32_32x32x16_bf16 v[98:113], v[168:171], v[114:117], v[98:113]
	v_exp_f32_e32 v220, v97
	v_add_f32_e32 v82, v212, v82
	v_add_f32_e32 v82, v214, v82
	v_add_f32_e32 v82, v216, v82
	s_waitcnt lgkmcnt(8)
	v_mfma_f32_32x32x16_bf16 v[66:81], v[242:245], v[114:117], v[66:81]
	v_add_f32_e32 v82, v218, v82
	v_add_f32_e32 v82, v220, v82
	v_add_f32_e32 v139, v82, v238
	v_cvt_pk_bf16_f32 v82, v176, v192
	v_cvt_pk_bf16_f32 v83, v194, v196
	s_waitcnt lgkmcnt(6)
	v_mfma_f32_32x32x16_bf16 v[2:17], v[222:225], v[180:183], v[2:17]
	ds_read_b64_tr_b16 v[230:231], v141 offset:0x1000
	ds_read_b64_tr_b16 v[232:233], v141 offset:0x1800
	ds_read_b64_tr_b16 v[234:235], v141 offset:0x1200
	ds_read_b64_tr_b16 v[236:237], v141 offset:0x1a00
	ds_read_b64_tr_b16 v[168:169], v141 offset:0x1400
	ds_read_b64_tr_b16 v[170:171], v141 offset:0x1c00
	ds_read_b64_tr_b16 v[172:173], v141 offset:0x1600
	ds_read_b64_tr_b16 v[174:175], v141 offset:0x1e00
	v_cvt_pk_bf16_f32 v84, v198, v200
	v_cvt_pk_bf16_f32 v85, v202, v204
	v_cvt_pk_bf16_f32 v86, v206, v208
	v_cvt_pk_bf16_f32 v87, v210, v212
	s_waitcnt lgkmcnt(12)
	v_mfma_f32_32x32x16_bf16 v[18:33], v[222:225], v[164:167], v[18:33]
	v_cvt_pk_bf16_f32 v88, v214, v216
	v_cvt_pk_bf16_f32 v89, v218, v220
	s_nop 0
	v_permlane32_swap_b32_e32 v82, v84
	s_waitcnt lgkmcnt(10)
	v_mfma_f32_32x32x16_bf16 v[34:49], v[222:225], v[184:187], v[34:49]
	v_permlane32_swap_b32_e32 v83, v85
	v_permlane32_swap_b32_e32 v86, v88
	v_permlane32_swap_b32_e32 v87, v89
	s_waitcnt lgkmcnt(8)
	v_mfma_f32_32x32x16_bf16 v[50:65], v[222:225], v[188:191], v[50:65]
	v_add_co_u32_e32 v90, vcc, s43, v136
	s_nop 1
	v_addc_co_u32_e32 v91, vcc, 0, v137, vcc
	v_add_co_u32_e32 v94, vcc, s46, v136
	s_nop 1
	v_addc_co_u32_e32 v95, vcc, 0, v137, vcc
	v_add_co_u32_e32 v130, vcc, s47, v150
	global_load_dwordx4 v[90:93], v[90:91], off
	s_nop 0
	s_waitcnt lgkmcnt(6)
; #define SBAR() __builtin_amdgcn_sched_barrier(0)
; #define SLOAD(i, k0) do { const char* vt_ = (const char*)Vh + (size_t)(k0) * 256; const char* kt_ = (const char*)Kh + (size_t)(k0) * 128; \
;     sr_[i].vs0 = *reinterpret_cast<const bf16x8*>(vt_ + voff0); sr_[i].vs1 = *reinterpret_cast<const bf16x8*>(vt_ + 32 * 256 + voff0); \
;     sr_[i].ks0 = *reinterpret_cast<const bf16x8*>(kt_ + koff0); } while (0)
; #define SWAIT() asm volatile("s_waitcnt vmcnt(0)" ::: "memory")
; __device__ __forceinline__ void qkt(f32x16& p0, f32x16& p1, const char* Ks, const bf16x8* qr, int r32, int hi) {
;     p0 = f32x16{}; p1 = f32x16{};
; #pragma unroll
;     for (int d0 = 0; d0 < 4; ++d0) { const int cb = (d0 * 16 + hi * 8) * 2;
;         const bf16x8 b0 = *reinterpret_cast<const bf16x8*>(Ks + KSWZ64(r32, cb));
;         const bf16x8 b1 = *reinterpret_cast<const bf16x8*>(Ks + KSWZ64(32 + r32, cb));
;         p0 = __builtin_amdgcn_mfma_f32_32x32x16_bf16(b0, qr[d0], p0, 0, 0, 0);
;         p1 = __builtin_amdgcn_mfma_f32_32x32x16_bf16(b1, qr[d0], p1, 0, 0, 0); }
; }
; template <int KS> __device__ __forceinline__ void pv_ks(f32x16* o, int vb, bf16x8 pa) {
;     const s16x4 l0 = tr_read<v_rd_off(0, KS, 0)>(vb), h0 = tr_read<v_rd_off(0, KS, 1)>(vb), l1 = tr_read<v_rd_off(1, KS, 0)>(vb), h1 = tr_read<v_rd_off(1, KS, 1)>(vb);
;     const s16x4 l2 = tr_read<v_rd_off(2, KS, 0)>(vb), h2 = tr_read<v_rd_off(2, KS, 1)>(vb), l3 = tr_read<v_rd_off(3, KS, 0)>(vb), h3 = tr_read<v_rd_off(3, KS, 1)>(vb);
;     asm volatile("s_waitcnt lgkmcnt(0)" ::: "memory"); SBAR();
;     ...
;     o[0] = __builtin_amdgcn_mfma_f32_32x32x16_bf16(pa, PK(l0, h0), o[0], 0, 0, 0);
;     o[1] = __builtin_amdgcn_mfma_f32_32x32x16_bf16(pa, PK(l1, h1), o[1], 0, 0, 0);
;     o[2] = __builtin_amdgcn_mfma_f32_32x32x16_bf16(pa, PK(l2, h2), o[2], 0, 0, 0);
;     o[3] = __builtin_amdgcn_mfma_f32_32x32x16_bf16(pa, PK(l3, h3), o[3], 0, 0, 0);
;     ...
; }
; __device__ __forceinline__ void attn_unit(const bf16* __restrict__ Qb, const bf16* __restrict__ Kh, const bf16* __restrict__ Vh, bf16* __restrict__ Ob, int seq, char* lds) {
;     ...
;         SLOAD(SE, (j + 2) * KVBLK); SBAR();
;         pv_ks<1>(o, vb0 + SHM_V, pa1); pv_ks<2>(o, vb0 + SHM_V, pa2); pv_ks<3>(o, vb0 + SHM_V, pa3); SBAR();
;         softHalf(pA0, l_reg, pa0, pa1); SBAR();
;         __syncthreads(); SWAIT(); SWRITE(1, SO);
;         __syncthreads();
	v_mfma_f32_32x32x16_bf16 v[2:17], v[226:229], v[230:233], v[2:17]
	ds_read_b64_tr_b16 v[180:181], v141 offset:0x2000
	ds_read_b64_tr_b16 v[182:183], v141 offset:0x2800
	ds_read_b64_tr_b16 v[184:185], v141 offset:0x2200
	ds_read_b64_tr_b16 v[186:187], v141 offset:0x2a00
	ds_read_b64_tr_b16 v[188:189], v141 offset:0x2400
	ds_read_b64_tr_b16 v[190:191], v141 offset:0x2c00
	ds_read_b64_tr_b16 v[222:223], v141 offset:0x2600
	ds_read_b64_tr_b16 v[224:225], v141 offset:0x2e00
	global_load_dwordx4 v[94:97], v[94:95], off
	v_addc_co_u32_e32 v131, vcc, 0, v151, vcc
	global_load_dwordx4 v[164:167], v[130:131], off
	v_exp_f32_e32 v239, v98
	v_exp_f32_e32 v241, v99
	s_waitcnt lgkmcnt(12)
	v_mfma_f32_32x32x16_bf16 v[18:33], v[226:229], v[234:237], v[18:33]
	v_exp_f32_e32 v242, v100
	v_exp_f32_e32 v243, v101
	v_exp_f32_e32 v244, v102
	s_waitcnt lgkmcnt(10)
	v_mfma_f32_32x32x16_bf16 v[34:49], v[226:229], v[168:171], v[34:49]
	v_exp_f32_e32 v98, v106
	v_add_f32_e32 v106, 0, v239
	v_exp_f32_e32 v245, v103
	v_add_f32_e32 v106, v241, v106
	s_waitcnt lgkmcnt(8)
	v_mfma_f32_32x32x16_bf16 v[50:65], v[226:229], v[172:175], v[50:65]
	v_exp_f32_e32 v246, v104
	v_add_f32_e32 v106, v242, v106
	v_exp_f32_e32 v247, v105
	v_add_f32_e32 v106, v243, v106
	v_add_f32_e32 v106, v244, v106
	s_waitcnt lgkmcnt(6)
	v_mfma_f32_32x32x16_bf16 v[2:17], v[82:85], v[180:183], v[2:17]
	ds_read_b64_tr_b16 v[230:231], v141 offset:0x3000
	ds_read_b64_tr_b16 v[232:233], v141 offset:0x3800
	ds_read_b64_tr_b16 v[234:235], v141 offset:0x3200
	ds_read_b64_tr_b16 v[236:237], v141 offset:0x3a00
	ds_read_b64_tr_b16 v[168:169], v141 offset:0x3400
	ds_read_b64_tr_b16 v[170:171], v141 offset:0x3c00
	ds_read_b64_tr_b16 v[172:173], v141 offset:0x3600
	ds_read_b64_tr_b16 v[174:175], v141 offset:0x3e00
	v_exp_f32_e32 v99, v107
	v_add_f32_e32 v106, v245, v106
	v_exp_f32_e32 v100, v108
	v_add_f32_e32 v106, v246, v106
	s_waitcnt lgkmcnt(12)
	v_mfma_f32_32x32x16_bf16 v[18:33], v[82:85], v[184:187], v[18:33]
	v_exp_f32_e32 v101, v109
	v_add_f32_e32 v106, v247, v106
	v_exp_f32_e32 v102, v110
	v_add_f32_e32 v106, v98, v106
	s_waitcnt lgkmcnt(10)
	v_mfma_f32_32x32x16_bf16 v[34:49], v[82:85], v[188:191], v[34:49]
	v_exp_f32_e32 v103, v111
	v_add_f32_e32 v106, v99, v106
	v_exp_f32_e32 v104, v112
	v_add_f32_e32 v106, v100, v106
	s_waitcnt lgkmcnt(8)
	v_mfma_f32_32x32x16_bf16 v[50:65], v[82:85], v[222:225], v[50:65]
	v_exp_f32_e32 v105, v113
	v_add_f32_e32 v106, v101, v106
	v_add_f32_e32 v106, v102, v106
	v_add_f32_e32 v106, v103, v106
	v_add_f32_e32 v106, v104, v106
	v_add_f32_e32 v106, v105, v106
	s_waitcnt lgkmcnt(6)
	v_mfma_f32_32x32x16_bf16 v[2:17], v[86:89], v[230:233], v[2:17]
	v_cvt_pk_bf16_f32 v134, v239, v241
	v_cvt_pk_bf16_f32 v135, v242, v243
	v_cvt_pk_bf16_f32 v136, v244, v245
	v_cvt_pk_bf16_f32 v137, v246, v247
	v_cvt_pk_bf16_f32 v130, v98, v99
	s_waitcnt lgkmcnt(4)
	v_mfma_f32_32x32x16_bf16 v[18:33], v[86:89], v[234:237], v[18:33]
	v_cvt_pk_bf16_f32 v131, v100, v101
	v_cvt_pk_bf16_f32 v132, v102, v103
	v_cvt_pk_bf16_f32 v133, v104, v105
	v_add_f32_e32 v139, v139, v106
	v_permlane32_swap_b32_e32 v134, v136
	s_waitcnt lgkmcnt(2)
	v_mfma_f32_32x32x16_bf16 v[34:49], v[86:89], v[168:171], v[34:49]
	v_permlane32_swap_b32_e32 v135, v137
	v_permlane32_swap_b32_e32 v130, v132
	v_permlane32_swap_b32_e32 v131, v133
	s_waitcnt lgkmcnt(0)
	v_mfma_f32_32x32x16_bf16 v[50:65], v[86:89], v[172:175], v[50:65]
	s_barrier
	s_waitcnt vmcnt(0)
	s_add_i32 s10, s10, 2
	v_lshl_add_u64 v[146:147], v[146:147], 0, s[0:1]
	s_cmp_gt_u32 s10, 32
	v_lshl_add_u64 v[148:149], v[148:149], 0, s[4:5]
	s_waitcnt vmcnt(2)
	ds_write_b128 v160, v[90:93] offset:16384
	s_waitcnt vmcnt(1)
	ds_write_b128 v161, v[94:97] offset:16384
	s_waitcnt vmcnt(0)
	ds_write_b128 v158, v[164:167] offset:40960
	s_waitcnt lgkmcnt(0)
	s_barrier
	s_cbranch_scc0 .LBB0_531
	v_and_b32_e32 v82, 0x3fffffc0, v143
	v_lshl_add_u32 v143, v82, 2, 0
	ds_read_b128 v[82:85], v157 offset:40960
	ds_read_b128 v[86:89], v157 offset:45056
	s_waitcnt lgkmcnt(1)
	v_mfma_f32_32x32x16_bf16 v[98:113], v[82:85], v[126:129], 0
	s_waitcnt lgkmcnt(0)
	v_mfma_f32_32x32x16_bf16 v[82:97], v[86:89], v[126:129], 0
	ds_read_b128 v[126:129], v159 offset:40960
	ds_read_b128 v[146:149], v159 offset:45056
	s_waitcnt lgkmcnt(1)
	v_mfma_f32_32x32x16_bf16 v[98:113], v[126:129], v[122:125], v[98:113]
	s_waitcnt lgkmcnt(0)
	v_mfma_f32_32x32x16_bf16 v[82:97], v[146:149], v[122:125], v[82:97]
	ds_read_b128 v[122:125], v162 offset:40960
	ds_read_b128 v[126:129], v162 offset:45056
	s_waitcnt lgkmcnt(1)
	v_mfma_f32_32x32x16_bf16 v[98:113], v[122:125], v[118:121], v[98:113]
	s_waitcnt lgkmcnt(0)
	v_mfma_f32_32x32x16_bf16 v[82:97], v[126:129], v[118:121], v[82:97]
	ds_read_b128 v[118:121], v163 offset:40960
	ds_read_b128 v[122:125], v163 offset:45056
	ds_read_b64_tr_b16 v[126:127], v156 offset:0
	ds_read_b64_tr_b16 v[128:129], v156 offset:0x800
	s_waitcnt lgkmcnt(1)
	v_mfma_f32_32x32x16_bf16 v[98:113], v[118:121], v[114:117], v[98:113]
	ds_read_b64_tr_b16 v[118:119], v156 offset:0x200
	ds_read_b64_tr_b16 v[120:121], v156 offset:0xa00
	ds_read_b64_tr_b16 v[146:147], v156 offset:0x400
	ds_read_b64_tr_b16 v[148:149], v156 offset:0xc00
	ds_read_b64_tr_b16 v[158:159], v156 offset:0x600
	ds_read_b64_tr_b16 v[160:161], v156 offset:0xe00
	s_waitcnt lgkmcnt(0)
	s_waitcnt lgkmcnt(0)
; __device__ __forceinline__ void softHalf(f32x16& p, float& l_reg, bf16x8& paLo, bf16x8& paHi) {
; #pragma unroll
;     for (int r = 0; r < 16; ++r) p[r] = __builtin_amdgcn_exp2f(p[r]);
;     float ps = 0;
; #pragma unroll
;     for (int r = 0; r < 16; ++r) ps += p[r];
;     l_reg += ps;
;     ...
;     PK4(p, 0, paLo); PK4(p, 8, paHi);
;     ...
; }
; __device__ __forceinline__ void qkt(f32x16& p0, f32x16& p1, const char* Ks, const bf16x8* qr, int r32, int hi) {
;     p0 = f32x16{}; p1 = f32x16{};
; #pragma unroll
;     for (int d0 = 0; d0 < 4; ++d0) { const int cb = (d0 * 16 + hi * 8) * 2;
;         const bf16x8 b0 = *reinterpret_cast<const bf16x8*>(Ks + KSWZ64(r32, cb));
;         const bf16x8 b1 = *reinterpret_cast<const bf16x8*>(Ks + KSWZ64(32 + r32, cb));
;         p0 = __builtin_amdgcn_mfma_f32_32x32x16_bf16(b0, qr[d0], p0, 0, 0, 0);
;         p1 = __builtin_amdgcn_mfma_f32_32x32x16_bf16(b1, qr[d0], p1, 0, 0, 0); }
; }
; __device__ __forceinline__ int v_st(int k, int c) { const int kk = (k & ~0xC) | ((k & 4) << 1) | ((k & 8) >> 1); return ((kk >> 3) * 4 + (c >> 5)) * 512 + ((kk & 7) * 32 + (c & 31)) * 2; }
; __device__ __forceinline__ int v_rd_base(int lane) { return ((lane & 3) << 3) | (((lane >> 2) & 3) << 6) | (((lane >> 4) & 1) << 5) | (((lane >> 5) & 1) << 8); }
; template <int OFF> __device__ __forceinline__ s16x4 tr_read(int vb) {
;     s16x4 r; asm volatile("ds_read_b64_tr_b16 %0, %1 offset:%2" : "=&v"(r) : "v"(vb), "i"(OFF) : "memory"); return r;
; }
; template <int D0> __device__ __forceinline__ void pv_one(f32x16& od, int vb, bf16x8 pa0, bf16x8 pa1, bf16x8 pa2, bf16x8 pa3) {
;     const s16x4 l0 = tr_read<v_rd_off(D0, 0, 0)>(vb), h0 = tr_read<v_rd_off(D0, 0, 1)>(vb), l1 = tr_read<v_rd_off(D0, 1, 0)>(vb), h1 = tr_read<v_rd_off(D0, 1, 1)>(vb);
;     const s16x4 l2 = tr_read<v_rd_off(D0, 2, 0)>(vb), h2 = tr_read<v_rd_off(D0, 2, 1)>(vb), l3 = tr_read<v_rd_off(D0, 3, 0)>(vb), h3 = tr_read<v_rd_off(D0, 3, 1)>(vb);
; __device__ __forceinline__ void attn_unit(const bf16* __restrict__ Qb, const bf16* __restrict__ Kh, const bf16* __restrict__ Vh, bf16* __restrict__ Ob, int seq, char* lds) {
;     ...
;     SBAR(); qkt(pB0, pB1, K_lds + SHM_K, qr, r32, hi); pv_ks<0>(o, vb0, pa0); SBAR();
;     softHalf(pA1, l_reg, pa2, pa3); SBAR();
;     pv_ks<1>(o, vb0, pa1); pv_ks<2>(o, vb0, pa2); pv_ks<3>(o, vb0, pa3); SBAR();
;     softHalf(pB0, l_reg, pa0, pa1); SBAR();
	v_mfma_f32_32x32x16_bf16 v[82:97], v[122:125], v[114:117], v[82:97]
	v_mfma_f32_32x32x16_bf16 v[2:17], v[134:137], v[126:129], v[2:17]
	v_mfma_f32_32x32x16_bf16 v[18:33], v[134:137], v[118:121], v[18:33]
	v_mfma_f32_32x32x16_bf16 v[34:49], v[134:137], v[146:149], v[34:49]
	v_mfma_f32_32x32x16_bf16 v[50:65], v[134:137], v[158:161], v[50:65]
	v_exp_f32_e32 v66, v66
	v_exp_f32_e32 v67, v67
	v_exp_f32_e32 v68, v68
	v_exp_f32_e32 v69, v69
	v_exp_f32_e32 v70, v70
	v_add_f32_e32 v114, 0, v66
	v_exp_f32_e32 v71, v71
	v_add_f32_e32 v114, v67, v114
	v_exp_f32_e32 v72, v72
	v_add_f32_e32 v114, v68, v114
	v_exp_f32_e32 v73, v73
	v_add_f32_e32 v114, v69, v114
	v_exp_f32_e32 v74, v74
	v_add_f32_e32 v114, v70, v114
	v_exp_f32_e32 v75, v75
	v_add_f32_e32 v114, v71, v114
	v_exp_f32_e32 v76, v76
	v_add_f32_e32 v114, v72, v114
	v_exp_f32_e32 v77, v77
	v_add_f32_e32 v114, v73, v114
	v_exp_f32_e32 v78, v78
	v_add_f32_e32 v114, v74, v114
	v_exp_f32_e32 v79, v79
	v_add_f32_e32 v114, v75, v114
	v_exp_f32_e32 v80, v80
	v_add_f32_e32 v114, v76, v114
	v_exp_f32_e32 v81, v81
	v_add_f32_e32 v114, v77, v114
	v_add_f32_e32 v114, v78, v114
	v_add_f32_e32 v114, v79, v114
	v_add_f32_e32 v114, v80, v114
	v_cvt_pk_bf16_f32 v66, v66, v67
	v_cvt_pk_bf16_f32 v67, v68, v69
	v_cvt_pk_bf16_f32 v68, v70, v71
	v_cvt_pk_bf16_f32 v69, v72, v73
	v_add_f32_e32 v114, v81, v114
	v_permlane32_swap_b32_e32 v66, v68
	v_permlane32_swap_b32_e32 v67, v69
	v_cvt_pk_bf16_f32 v70, v74, v75
	v_cvt_pk_bf16_f32 v71, v76, v77
	v_cvt_pk_bf16_f32 v72, v78, v79
	v_cvt_pk_bf16_f32 v73, v80, v81
	v_add_f32_e32 v126, v139, v114
	v_permlane32_swap_b32_e32 v70, v72
	v_permlane32_swap_b32_e32 v71, v73
	ds_read_b64_tr_b16 v[74:75], v156 offset:0x1000
	ds_read_b64_tr_b16 v[76:77], v156 offset:0x1800
	ds_read_b64_tr_b16 v[78:79], v156 offset:0x1200
	ds_read_b64_tr_b16 v[80:81], v156 offset:0x1a00
	ds_read_b64_tr_b16 v[114:115], v156 offset:0x1400
	ds_read_b64_tr_b16 v[116:117], v156 offset:0x1c00
	ds_read_b64_tr_b16 v[118:119], v156 offset:0x1600
	ds_read_b64_tr_b16 v[120:121], v156 offset:0x1e00
	s_waitcnt lgkmcnt(0)
	s_nop 0
	v_mfma_f32_32x32x16_bf16 v[2:17], v[130:133], v[74:77], v[2:17]
	ds_read_b64_tr_b16 v[74:75], v156 offset:0x2000
	ds_read_b64_tr_b16 v[76:77], v156 offset:0x2800
	v_mfma_f32_32x32x16_bf16 v[18:33], v[130:133], v[78:81], v[18:33]
	ds_read_b64_tr_b16 v[78:79], v156 offset:0x2200
	ds_read_b64_tr_b16 v[80:81], v156 offset:0x2a00
	v_mfma_f32_32x32x16_bf16 v[34:49], v[130:133], v[114:117], v[34:49]
	ds_read_b64_tr_b16 v[114:115], v156 offset:0x2400
	ds_read_b64_tr_b16 v[116:117], v156 offset:0x2c00
	ds_read_b64_tr_b16 v[122:123], v156 offset:0x2600
	ds_read_b64_tr_b16 v[124:125], v156 offset:0x2e00
	s_waitcnt lgkmcnt(0)
	v_mfma_f32_32x32x16_bf16 v[50:65], v[130:133], v[118:121], v[50:65]
	v_mfma_f32_32x32x16_bf16 v[2:17], v[66:69], v[74:77], v[2:17]
	ds_read_b64_tr_b16 v[74:75], v156 offset:0x3000
	ds_read_b64_tr_b16 v[76:77], v156 offset:0x3800
	v_mfma_f32_32x32x16_bf16 v[18:33], v[66:69], v[78:81], v[18:33]
	ds_read_b64_tr_b16 v[78:79], v156 offset:0x3200
	ds_read_b64_tr_b16 v[80:81], v156 offset:0x3a00
	v_mfma_f32_32x32x16_bf16 v[34:49], v[66:69], v[114:117], v[34:49]
	ds_read_b64_tr_b16 v[114:115], v156 offset:0x3400
	ds_read_b64_tr_b16 v[116:117], v156 offset:0x3c00
	ds_read_b64_tr_b16 v[118:119], v156 offset:0x3600
	ds_read_b64_tr_b16 v[120:121], v156 offset:0x3e00
	s_waitcnt lgkmcnt(0)
	v_mfma_f32_32x32x16_bf16 v[50:65], v[66:69], v[122:125], v[50:65]
	v_mfma_f32_32x32x16_bf16 v[2:17], v[70:73], v[74:77], v[2:17]
	v_mfma_f32_32x32x16_bf16 v[18:33], v[70:73], v[78:81], v[18:33]
	v_mfma_f32_32x32x16_bf16 v[34:49], v[70:73], v[114:117], v[34:49]
	v_mfma_f32_32x32x16_bf16 v[50:65], v[70:73], v[118:121], v[50:65]
	v_exp_f32_e32 v66, v98
	v_exp_f32_e32 v67, v99
	v_exp_f32_e32 v68, v100
	v_exp_f32_e32 v69, v101
	v_exp_f32_e32 v70, v102
	v_add_f32_e32 v98, 0, v66
	v_exp_f32_e32 v71, v103
	v_add_f32_e32 v98, v67, v98
	v_exp_f32_e32 v72, v104
	v_add_f32_e32 v98, v68, v98
	v_exp_f32_e32 v73, v105
	v_add_f32_e32 v98, v69, v98
	v_exp_f32_e32 v74, v106
	v_add_f32_e32 v98, v70, v98
	v_exp_f32_e32 v75, v107
	v_add_f32_e32 v98, v71, v98
	v_exp_f32_e32 v76, v108
	v_add_f32_e32 v98, v72, v98
	v_exp_f32_e32 v77, v109
	v_add_f32_e32 v98, v73, v98
	v_exp_f32_e32 v78, v110
	v_add_f32_e32 v98, v74, v98
	v_exp_f32_e32 v79, v111
	v_add_f32_e32 v98, v75, v98
	v_exp_f32_e32 v80, v112
	v_add_f32_e32 v98, v76, v98
	v_exp_f32_e32 v81, v113
	v_add_f32_e32 v98, v77, v98
	v_add_f32_e32 v98, v78, v98
	v_add_f32_e32 v98, v79, v98
	v_add_f32_e32 v98, v80, v98
	v_cvt_pk_bf16_f32 v66, v66, v67
	v_cvt_pk_bf16_f32 v67, v68, v69
	v_cvt_pk_bf16_f32 v68, v70, v71
	v_cvt_pk_bf16_f32 v69, v72, v73
	v_add_f32_e32 v98, v81, v98
	v_permlane32_swap_b32_e32 v66, v68
	v_permlane32_swap_b32_e32 v67, v69
	v_cvt_pk_bf16_f32 v70, v74, v75
	v_cvt_pk_bf16_f32 v71, v76, v77
	v_cvt_pk_bf16_f32 v72, v78, v79
	v_cvt_pk_bf16_f32 v73, v80, v81
	v_add_f32_e32 v106, v126, v98
	v_permlane32_swap_b32_e32 v70, v72
	v_permlane32_swap_b32_e32 v71, v73
	ds_read_b64_tr_b16 v[74:75], v141 offset:0
	ds_read_b64_tr_b16 v[76:77], v141 offset:0x800
	ds_read_b64_tr_b16 v[78:79], v141 offset:0x200
	ds_read_b64_tr_b16 v[80:81], v141 offset:0xa00
	ds_read_b64_tr_b16 v[98:99], v141 offset:0x400
	ds_read_b64_tr_b16 v[100:101], v141 offset:0xc00
	ds_read_b64_tr_b16 v[102:103], v141 offset:0x600
	ds_read_b64_tr_b16 v[104:105], v141 offset:0xe00
	s_waitcnt lgkmcnt(0)
; #define SBAR() __builtin_amdgcn_sched_barrier(0)
; #define SBAR() __builtin_amdgcn_sched_barrier(0)
; __device__ __forceinline__ void attn_unit(const bf16* __restrict__ Qb, const bf16* __restrict__ Kh, const bf16* __restrict__ Vh, bf16* __restrict__ Ob, int seq, char* lds) {
;     ...
;     pv_ks<0>(o, vb0 + SHM_V, pa0); SBAR();
;     softHalf(pB1, l_reg, pa2, pa3); SBAR();
;     pv_ks<1>(o, vb0 + SHM_V, pa1); pv_ks<2>(o, vb0 + SHM_V, pa2); pv_ks<3>(o, vb0 + SHM_V, pa3);
;     { auto rr = __builtin_amdgcn_permlane32_swap(__float_as_uint(l_reg), __float_as_uint(l_reg), false, false); l_reg = __uint_as_float(rr[0]) + __uint_as_float(rr[1]); }
;     if (hi == 0) wsf[r32] = l_reg; asm volatile("s_waitcnt lgkmcnt(0)" ::: "memory");
	s_nop 0
	v_mfma_f32_32x32x16_bf16 v[2:17], v[66:69], v[74:77], v[2:17]
	v_mfma_f32_32x32x16_bf16 v[18:33], v[66:69], v[78:81], v[18:33]
	v_mfma_f32_32x32x16_bf16 v[34:49], v[66:69], v[98:101], v[34:49]
	v_mfma_f32_32x32x16_bf16 v[50:65], v[66:69], v[102:105], v[50:65]
	v_exp_f32_e32 v67, v82
	v_exp_f32_e32 v68, v83
	v_exp_f32_e32 v69, v84
	v_exp_f32_e32 v75, v85
	v_exp_f32_e32 v76, v86
	v_add_f32_e32 v66, 0, v67
	v_exp_f32_e32 v77, v87
	v_add_f32_e32 v66, v68, v66
	v_exp_f32_e32 v78, v88
	v_add_f32_e32 v66, v69, v66
	v_exp_f32_e32 v79, v89
	v_add_f32_e32 v66, v75, v66
	v_exp_f32_e32 v80, v90
	v_add_f32_e32 v66, v76, v66
	v_exp_f32_e32 v81, v91
	v_add_f32_e32 v66, v77, v66
	v_exp_f32_e32 v82, v92
	v_add_f32_e32 v66, v78, v66
	v_exp_f32_e32 v83, v93
	v_add_f32_e32 v66, v79, v66
	v_exp_f32_e32 v84, v94
	v_add_f32_e32 v66, v80, v66
	v_exp_f32_e32 v85, v95
	v_add_f32_e32 v66, v81, v66
	v_exp_f32_e32 v86, v96
	v_add_f32_e32 v66, v82, v66
	v_exp_f32_e32 v87, v97
	v_add_f32_e32 v66, v83, v66
	v_add_f32_e32 v66, v84, v66
	v_add_f32_e32 v66, v85, v66
	v_add_f32_e32 v66, v86, v66
	v_add_f32_e32 v66, v87, v66
	v_add_f32_e32 v66, v66, v106
	v_cvt_pk_bf16_f32 v74, v67, v68
	v_cvt_pk_bf16_f32 v75, v69, v75
	v_cvt_pk_bf16_f32 v76, v76, v77
	v_cvt_pk_bf16_f32 v77, v78, v79
	v_cvt_pk_bf16_f32 v78, v80, v81
	v_cvt_pk_bf16_f32 v79, v82, v83
	v_cvt_pk_bf16_f32 v80, v84, v85
	v_cvt_pk_bf16_f32 v81, v86, v87
	s_nop 0
	v_permlane32_swap_b32_e32 v74, v76
	v_permlane32_swap_b32_e32 v75, v77
	v_permlane32_swap_b32_e32 v78, v80
	v_permlane32_swap_b32_e32 v79, v81
	ds_read_b64_tr_b16 v[82:83], v141 offset:0x1000
	ds_read_b64_tr_b16 v[84:85], v141 offset:0x1800
	ds_read_b64_tr_b16 v[86:87], v141 offset:0x1200
	ds_read_b64_tr_b16 v[88:89], v141 offset:0x1a00
	ds_read_b64_tr_b16 v[90:91], v141 offset:0x1400
	ds_read_b64_tr_b16 v[92:93], v141 offset:0x1c00
	ds_read_b64_tr_b16 v[94:95], v141 offset:0x1600
	ds_read_b64_tr_b16 v[96:97], v141 offset:0x1e00
	s_waitcnt lgkmcnt(0)
	s_nop 0
	v_mfma_f32_32x32x16_bf16 v[2:17], v[70:73], v[82:85], v[2:17]
	ds_read_b64_tr_b16 v[82:83], v141 offset:0x2000
	ds_read_b64_tr_b16 v[84:85], v141 offset:0x2800
	v_mfma_f32_32x32x16_bf16 v[18:33], v[70:73], v[86:89], v[18:33]
	ds_read_b64_tr_b16 v[86:87], v141 offset:0x2200
	ds_read_b64_tr_b16 v[88:89], v141 offset:0x2a00
	v_mfma_f32_32x32x16_bf16 v[34:49], v[70:73], v[90:93], v[34:49]
	ds_read_b64_tr_b16 v[90:91], v141 offset:0x2400
	ds_read_b64_tr_b16 v[92:93], v141 offset:0x2c00
	ds_read_b64_tr_b16 v[98:99], v141 offset:0x2600
	ds_read_b64_tr_b16 v[100:101], v141 offset:0x2e00
	s_waitcnt lgkmcnt(0)
	v_mfma_f32_32x32x16_bf16 v[50:65], v[70:73], v[94:97], v[50:65]
	ds_read_b64_tr_b16 v[68:69], v141 offset:0x3000
	ds_read_b64_tr_b16 v[70:71], v141 offset:0x3800
	v_mfma_f32_32x32x16_bf16 v[2:17], v[74:77], v[82:85], v[2:17]
	ds_read_b64_tr_b16 v[82:83], v141 offset:0x3200
	ds_read_b64_tr_b16 v[84:85], v141 offset:0x3a00
	v_mfma_f32_32x32x16_bf16 v[18:33], v[74:77], v[86:89], v[18:33]
	ds_read_b64_tr_b16 v[86:87], v141 offset:0x3400
	ds_read_b64_tr_b16 v[88:89], v141 offset:0x3c00
	v_mfma_f32_32x32x16_bf16 v[34:49], v[74:77], v[90:93], v[34:49]
	ds_read_b64_tr_b16 v[90:91], v141 offset:0x3600
	ds_read_b64_tr_b16 v[92:93], v141 offset:0x3e00
	s_waitcnt lgkmcnt(0)
	v_mfma_f32_32x32x16_bf16 v[50:65], v[74:77], v[98:101], v[50:65]
	v_mfma_f32_32x32x16_bf16 v[2:17], v[78:81], v[68:71], v[2:17]
	v_mov_b32_e32 v67, v66
	s_nop 1
	v_permlane32_swap_b32_e32 v66, v67
	v_cmp_gt_u32_e32 vcc, 32, v145
	v_mfma_f32_32x32x16_bf16 v[18:33], v[78:81], v[82:85], v[18:33]
	v_mfma_f32_32x32x16_bf16 v[34:49], v[78:81], v[86:89], v[34:49]
	v_mfma_f32_32x32x16_bf16 v[50:65], v[78:81], v[90:93], v[50:65]
	s_and_saveexec_b64 s[10:11], vcc
	s_cbranch_execz .LBB0_529
	v_add_f32_e32 v66, v66, v67
	v_lshl_add_u32 v67, v153, 2, v143
	ds_write_b32 v67, v66 offset:49152
	s_branch .LBB0_529
